# GQA q/k norm phase: 85 serialized item iterations -> 17 batches of 5 with loads up front, DPP row-reduce + readlane instead of 6 bpermute hops
# speedup vs baseline: 1.0024x; 1.0024x over previous
; __global__ void __launch_bounds__(512) mk_fwd(Params P) {
;     ...
;             const float* QKR = (const float*)BIG; bf16_t* Qb = (bf16_t*)(BIG + 3 * U1); bf16_t* Kb = (bf16_t*)(BIG + 5 * U1);
;             const float* tab = ROPE + ROPE32; const int jj = lane & 31;
;             const float gq0 = P.in[23][lane], gq1 = P.in[23][lane + 64], gk0 = P.in[24][lane], gk1 = P.in[24][lane + 64];
;             for (int it = gw; it < M * 10; it += NGW) { const int row = it / 10, slot = it - row * 10; const int bi = row / TB, rr = row - bi * TB;
;                 const float* src = QKR + (size_t)row * 1280 + slot * 128;
;                 float x0 = __builtin_nontemporal_load(&src[lane]), x1 = __builtin_nontemporal_load(&src[lane + 64]);
;                 const float rinv = rsqrtf(wave_sum(x0 * x0 + x1 * x1) * (1.f / 128.f) + EPS);
;                 x0 = x0 * rinv * (slot < 8 ? gq0 : gk0); x1 = x1 * rinv * (slot < 8 ? gq1 : gk1);
;                 if (rr >= CTXL) { const int t = rr - CTXL, pr = t >> 6, pc = t & 63;
;                     const float c0 = tab[(pr * 32 + jj) * 2], s0 = tab[(pr * 32 + jj) * 2 + 1], c1 = tab[(pc * 32 + jj) * 2], s1 = tab[(pc * 32 + jj) * 2 + 1];
.LBB0_25:
	s_cmp_eq_u32 s93, 5
	s_cselect_b64 s[6:7], -1, 0
	s_cmp_lt_u32 s77, 13
	s_cselect_b64 s[38:39], -1, 0
	s_cmp_gt_u32 s77, 12
	s_cselect_b64 s[54:55], -1, 0
	s_and_b64 s[12:13], s[6:7], s[38:39]
	s_and_b64 vcc, exec, s[12:13]
	s_cbranch_vccnz .LBB0_82
	s_cmp_eq_u32 s93, 6
	s_cselect_b64 s[10:11], -1, 0
	s_sub_i32 s3, s77, 35
	s_cmp_lt_u32 s3, 11
	s_cselect_b64 s[8:9], -1, 0
	s_and_b64 s[12:13], s[10:11], s[8:9]
	s_andn2_b64 vcc, exec, s[12:13]
	s_mov_b64 s[12:13], -1
	s_cbranch_vccz .LBB0_82
	s_and_b64 s[12:13], s[10:11], s[38:39]
	s_andn2_b64 vcc, exec, s[12:13]
	s_mov_b64 s[12:13], -1
	s_cbranch_vccz .LBB0_77
	s_add_i32 s3, s77, -13
	s_cmp_lt_u32 s3, 11
	s_cselect_b64 s[12:13], -1, 0
	s_and_b64 s[14:15], s[6:7], s[12:13]
	s_andn2_b64 vcc, exec, s[14:15]
	s_mov_b64 s[14:15], -1
	s_cbranch_vccz .LBB0_65
	s_and_b64 s[12:13], s[10:11], s[12:13]
	s_andn2_b64 vcc, exec, s[12:13]
	s_mov_b64 s[12:13], -1
	s_cbranch_vccz .LBB0_60
	s_sub_i32 s3, s77, 24
	s_cmp_lt_u32 s3, 11
	s_cselect_b64 s[12:13], -1, 0
	s_and_b64 s[14:15], s[6:7], s[12:13]
	s_andn2_b64 vcc, exec, s[14:15]
	s_mov_b64 s[14:15], -1
	s_cbranch_vccz .LBB0_48
	s_and_b64 s[10:11], s[10:11], s[12:13]
	s_andn2_b64 vcc, exec, s[10:11]
	s_mov_b64 s[10:11], -1
	s_cbranch_vccz .LBB0_43
	s_and_b64 s[6:7], s[6:7], s[8:9]
	s_andn2_b64 vcc, exec, s[6:7]
	s_cbranch_vccnz .LBB0_42
	s_cmp_gt_i32 s58, 0x2a7ff
	s_cbranch_scc1 .LBB0_42
	v_readlane_b32 s8, v253, 53
	v_lshlrev_b32_e32 v2, 2, v148
	v_readlane_b32 s10, v253, 55
	v_readlane_b32 s11, v253, 56
	v_readlane_b32 s9, v253, 54
	s_waitcnt lgkmcnt(0)
	s_nop 2
	global_load_dword v1, v2, s[10:11] offset:256
	global_load_dword v0, v2, s[10:11]
	global_load_dword v3, v2, s[8:9] offset:256
	s_nop 0
	global_load_dword v2, v2, s[8:9]
	v_cmp_lt_i32_e32 vcc, v189, v188
	s_add_u32 s3, s0, 0x10369000
	s_addc_u32 s20, s1, 0
	s_waitcnt vmcnt(0)
	v_cndmask_b32_e32 v4, v187, v189, vcc
	v_cmp_lt_i32_e32 vcc, v190, v188
	v_lshlrev_b32_e32 v11, 2, v4
	s_add_u32 s10, s0, 0x6c57000
	v_cndmask_b32_e32 v4, v187, v190, vcc
	v_cmp_lt_i32_e32 vcc, v191, v188
	v_lshlrev_b32_e32 v12, 2, v4
	s_addc_u32 s11, s1, 0
	v_cndmask_b32_e32 v4, v187, v191, vcc
	v_cmp_lt_i32_e32 vcc, v192, v188
	v_lshlrev_b32_e32 v13, 2, v4
	v_and_b32_e32 v10, 31, v146
	v_cndmask_b32_e32 v4, v187, v192, vcc
	v_cmp_lt_i32_e32 vcc, v193, v188
	v_lshlrev_b32_e32 v14, 2, v4
	s_lshl_b32 s8, s2, 10
	v_cndmask_b32_e32 v4, v187, v193, vcc
	v_cmp_lt_i32_e32 vcc, v194, v188
	v_lshlrev_b32_e32 v15, 2, v4
	s_lshl_b32 s9, s46, 7
	v_cndmask_b32_e32 v4, v187, v194, vcc
	v_lshlrev_b32_e32 v16, 2, v4
	v_mov_b32_e32 v4, 0xffffff00
	v_lshl_or_b32 v17, v10, 1, v4
	v_cmp_gt_u32_e64 s[6:7], 32, v148
	s_add_i32 s21, s8, s9
	v_lshlrev_b32_e32 v4, 2, v148
	v_mov_b32_e32 v5, v145
	v_lshlrev_b32_e32 v6, 1, v148
	v_mov_b32_e32 v7, v145
	s_mov_b32 s22, s58
	v_readlane_b32 s12, v253, 57
	v_readlane_b32 s13, v253, 58
	v_readlane_b32 s14, v253, 59
	v_readlane_b32 s15, v253, 60
	v_lshlrev_b32_e32 v9, 3, v10
	v_xor_b32_e32 v12, 32, v148
	v_lshlrev_b32_e32 v12, 2, v12
.Lgq_batch_test:
	s_mul_i32 s8, s42, 4
	s_add_u32 s8, s22, s8
	s_cmp_lt_u32 s8, 0x2a800
	s_cbranch_scc0 .Lgq_tail
	s_mov_b32 s12, s22
	s_mul_hi_u32 s13, s12, 0x66666667
	s_lshr_b32 s13, s13, 2
	s_mul_i32 s9, s13, 10
	s_sub_u32 s9, s12, s9
	s_lshl_b32 s14, s12, 9
	s_add_u32 s14, s90, s14
	s_addc_u32 s15, s91, 0
	global_load_dword v20, v4, s[14:15] nt
	global_load_dword v21, v4, s[14:15] offset:256 nt
	s_mul_hi_u32 s8, s12, 0x60606061
	s_lshr_b32 s8, s8, 14
	s_mul_i32 s8, s8, 0x1100
	s_sub_u32 s8, s13, s8
	s_sub_u32 s8, s8, 0x100
	s_cmp_ge_i32 s8, 0
	s_cbranch_scc0 .Lgq_b_nolat0
	s_lshr_b32 s14, s8, 6
	s_lshl_b32 s14, s14, 8
	s_add_u32 s14, s10, s14
	s_addc_u32 s15, s11, 0
	global_load_dwordx2 v[24:25], v9, s[14:15]
	s_and_b32 s14, s8, 63
	s_lshl_b32 s14, s14, 8
	s_add_u32 s14, s10, s14
	s_addc_u32 s15, s11, 0
	global_load_dwordx2 v[26:27], v9, s[14:15]
.Lgq_b_nolat0:
	s_mul_i32 s12, s42, 1
	s_add_u32 s12, s22, s12
	s_mul_hi_u32 s13, s12, 0x66666667
	s_lshr_b32 s13, s13, 2
	s_mul_i32 s9, s13, 10
	s_sub_u32 s9, s12, s9
	s_lshl_b32 s14, s12, 9
	s_add_u32 s14, s90, s14
	s_addc_u32 s15, s91, 0
	global_load_dword v32, v4, s[14:15] nt
	global_load_dword v33, v4, s[14:15] offset:256 nt
	s_mul_hi_u32 s8, s12, 0x60606061
	s_lshr_b32 s8, s8, 14
	s_mul_i32 s8, s8, 0x1100
	s_sub_u32 s8, s13, s8
	s_sub_u32 s8, s8, 0x100
	s_cmp_ge_i32 s8, 0
	s_cbranch_scc0 .Lgq_b_nolat1
	s_lshr_b32 s14, s8, 6
	s_lshl_b32 s14, s14, 8
	s_add_u32 s14, s10, s14
	s_addc_u32 s15, s11, 0
	global_load_dwordx2 v[36:37], v9, s[14:15]
	s_and_b32 s14, s8, 63
	s_lshl_b32 s14, s14, 8
	s_add_u32 s14, s10, s14
	s_addc_u32 s15, s11, 0
	global_load_dwordx2 v[38:39], v9, s[14:15]
.Lgq_b_nolat1:
	s_mul_i32 s12, s42, 2
	s_add_u32 s12, s22, s12
	s_mul_hi_u32 s13, s12, 0x66666667
	s_lshr_b32 s13, s13, 2
	s_mul_i32 s9, s13, 10
	s_sub_u32 s9, s12, s9
	s_lshl_b32 s14, s12, 9
	s_add_u32 s14, s90, s14
	s_addc_u32 s15, s91, 0
	global_load_dword v44, v4, s[14:15] nt
	global_load_dword v45, v4, s[14:15] offset:256 nt
	s_mul_hi_u32 s8, s12, 0x60606061
	s_lshr_b32 s8, s8, 14
	s_mul_i32 s8, s8, 0x1100
	s_sub_u32 s8, s13, s8
	s_sub_u32 s8, s8, 0x100
	s_cmp_ge_i32 s8, 0
	s_cbranch_scc0 .Lgq_b_nolat2
	s_lshr_b32 s14, s8, 6
	s_lshl_b32 s14, s14, 8
	s_add_u32 s14, s10, s14
	s_addc_u32 s15, s11, 0
	global_load_dwordx2 v[48:49], v9, s[14:15]
	s_and_b32 s14, s8, 63
	s_lshl_b32 s14, s14, 8
	s_add_u32 s14, s10, s14
	s_addc_u32 s15, s11, 0
	global_load_dwordx2 v[50:51], v9, s[14:15]
; __device__ __forceinline__ float wave_sum(float v) {
; #pragma unroll
;     for (int o = 1; o < 64; o <<= 1) v += __shfl_xor(v, o);
;     return v;
; __global__ void __launch_bounds__(512) mk_fwd(Params P) {
;     ...
;             for (int it = gw; it < M * 10; it += NGW) { const int row = it / 10, slot = it - row * 10; const int bi = row / TB, rr = row - bi * TB;
;                 const float* src = QKR + (size_t)row * 1280 + slot * 128;
;                 float x0 = __builtin_nontemporal_load(&src[lane]), x1 = __builtin_nontemporal_load(&src[lane + 64]);
;                 const float rinv = rsqrtf(wave_sum(x0 * x0 + x1 * x1) * (1.f / 128.f) + EPS);
;                 x0 = x0 * rinv * (slot < 8 ? gq0 : gk0); x1 = x1 * rinv * (slot < 8 ? gq1 : gk1);
.Lgq_b_nolat2:
	s_mul_i32 s12, s42, 3
	s_add_u32 s12, s22, s12
	s_mul_hi_u32 s13, s12, 0x66666667
	s_lshr_b32 s13, s13, 2
	s_mul_i32 s9, s13, 10
	s_sub_u32 s9, s12, s9
	s_lshl_b32 s14, s12, 9
	s_add_u32 s14, s90, s14
	s_addc_u32 s15, s91, 0
	global_load_dword v56, v4, s[14:15] nt
	global_load_dword v57, v4, s[14:15] offset:256 nt
	s_mul_hi_u32 s8, s12, 0x60606061
	s_lshr_b32 s8, s8, 14
	s_mul_i32 s8, s8, 0x1100
	s_sub_u32 s8, s13, s8
	s_sub_u32 s8, s8, 0x100
	s_cmp_ge_i32 s8, 0
	s_cbranch_scc0 .Lgq_b_nolat3
	s_lshr_b32 s14, s8, 6
	s_lshl_b32 s14, s14, 8
	s_add_u32 s14, s10, s14
	s_addc_u32 s15, s11, 0
	global_load_dwordx2 v[60:61], v9, s[14:15]
	s_and_b32 s14, s8, 63
	s_lshl_b32 s14, s14, 8
	s_add_u32 s14, s10, s14
	s_addc_u32 s15, s11, 0
	global_load_dwordx2 v[62:63], v9, s[14:15]
.Lgq_b_nolat3:
	s_mul_i32 s12, s42, 4
	s_add_u32 s12, s22, s12
	s_mul_hi_u32 s13, s12, 0x66666667
	s_lshr_b32 s13, s13, 2
	s_mul_i32 s9, s13, 10
	s_sub_u32 s9, s12, s9
	s_lshl_b32 s14, s12, 9
	s_add_u32 s14, s90, s14
	s_addc_u32 s15, s91, 0
	global_load_dword v68, v4, s[14:15] nt
	global_load_dword v69, v4, s[14:15] offset:256 nt
	s_mul_hi_u32 s8, s12, 0x60606061
	s_lshr_b32 s8, s8, 14
	s_mul_i32 s8, s8, 0x1100
	s_sub_u32 s8, s13, s8
	s_sub_u32 s8, s8, 0x100
	s_cmp_ge_i32 s8, 0
	s_cbranch_scc0 .Lgq_b_nolat4
	s_lshr_b32 s14, s8, 6
	s_lshl_b32 s14, s14, 8
	s_add_u32 s14, s10, s14
	s_addc_u32 s15, s11, 0
	global_load_dwordx2 v[72:73], v9, s[14:15]
	s_and_b32 s14, s8, 63
	s_lshl_b32 s14, s14, 8
	s_add_u32 s14, s10, s14
	s_addc_u32 s15, s11, 0
	global_load_dwordx2 v[74:75], v9, s[14:15]
.Lgq_b_nolat4:
	s_waitcnt vmcnt(0)
	v_pk_mul_f32 v[22:23], v[20:21], v[20:21]
	v_pk_mul_f32 v[34:35], v[32:33], v[32:33]
	v_pk_mul_f32 v[46:47], v[44:45], v[44:45]
	v_pk_mul_f32 v[58:59], v[56:57], v[56:57]
	v_pk_mul_f32 v[70:71], v[68:69], v[68:69]
	v_add_f32_e32 v22, v22, v23
	v_add_f32_e32 v34, v34, v35
	v_add_f32_e32 v46, v46, v47
	v_add_f32_e32 v58, v58, v59
	v_add_f32_e32 v70, v70, v71
	s_nop 1
	v_add_f32_dpp v22, v22, v22 quad_perm:[1,0,3,2] row_mask:0xf bank_mask:0xf
	s_nop 1
	v_add_f32_dpp v34, v34, v34 quad_perm:[1,0,3,2] row_mask:0xf bank_mask:0xf
	s_nop 1
	v_add_f32_dpp v46, v46, v46 quad_perm:[1,0,3,2] row_mask:0xf bank_mask:0xf
	s_nop 1
	v_add_f32_dpp v58, v58, v58 quad_perm:[1,0,3,2] row_mask:0xf bank_mask:0xf
	s_nop 1
	v_add_f32_dpp v70, v70, v70 quad_perm:[1,0,3,2] row_mask:0xf bank_mask:0xf
	s_nop 1
	v_add_f32_dpp v22, v22, v22 quad_perm:[2,3,0,1] row_mask:0xf bank_mask:0xf
	s_nop 1
	v_add_f32_dpp v34, v34, v34 quad_perm:[2,3,0,1] row_mask:0xf bank_mask:0xf
	s_nop 1
	v_add_f32_dpp v46, v46, v46 quad_perm:[2,3,0,1] row_mask:0xf bank_mask:0xf
	s_nop 1
	v_add_f32_dpp v58, v58, v58 quad_perm:[2,3,0,1] row_mask:0xf bank_mask:0xf
	s_nop 1
	v_add_f32_dpp v70, v70, v70 quad_perm:[2,3,0,1] row_mask:0xf bank_mask:0xf
	s_nop 1
	v_add_f32_dpp v22, v22, v22 row_half_mirror row_mask:0xf bank_mask:0xf
	s_nop 1
	v_add_f32_dpp v34, v34, v34 row_half_mirror row_mask:0xf bank_mask:0xf
	s_nop 1
	v_add_f32_dpp v46, v46, v46 row_half_mirror row_mask:0xf bank_mask:0xf
	s_nop 1
	v_add_f32_dpp v58, v58, v58 row_half_mirror row_mask:0xf bank_mask:0xf
	s_nop 1
	v_add_f32_dpp v70, v70, v70 row_half_mirror row_mask:0xf bank_mask:0xf
	s_nop 1
	v_add_f32_dpp v22, v22, v22 row_mirror row_mask:0xf bank_mask:0xf
	s_nop 1
	v_add_f32_dpp v34, v34, v34 row_mirror row_mask:0xf bank_mask:0xf
	s_nop 1
	v_add_f32_dpp v46, v46, v46 row_mirror row_mask:0xf bank_mask:0xf
	s_nop 1
	v_add_f32_dpp v58, v58, v58 row_mirror row_mask:0xf bank_mask:0xf
	s_nop 1
	v_add_f32_dpp v70, v70, v70 row_mirror row_mask:0xf bank_mask:0xf
	s_nop 0
	v_readlane_b32 s8, v22, 0
	v_readlane_b32 s9, v22, 16
	v_readlane_b32 s12, v22, 32
	v_readlane_b32 s13, v22, 48
	s_nop 0
	v_mov_b32_e32 v22, s9
	v_add_f32_e32 v22, s8, v22
	v_mov_b32_e32 v23, s13
	v_add_f32_e32 v23, s12, v23
	v_add_f32_e32 v22, v22, v23
	s_nop 0
	v_readlane_b32 s8, v34, 0
	v_readlane_b32 s9, v34, 16
	v_readlane_b32 s12, v34, 32
	v_readlane_b32 s13, v34, 48
	s_nop 0
	v_mov_b32_e32 v34, s9
	v_add_f32_e32 v34, s8, v34
	v_mov_b32_e32 v35, s13
	v_add_f32_e32 v35, s12, v35
	v_add_f32_e32 v34, v34, v35
	s_nop 0
	v_readlane_b32 s8, v46, 0
	v_readlane_b32 s9, v46, 16
	v_readlane_b32 s12, v46, 32
	v_readlane_b32 s13, v46, 48
	s_nop 0
	v_mov_b32_e32 v46, s9
	v_add_f32_e32 v46, s8, v46
	v_mov_b32_e32 v47, s13
	v_add_f32_e32 v47, s12, v47
	v_add_f32_e32 v46, v46, v47
	s_nop 0
	v_readlane_b32 s8, v58, 0
	v_readlane_b32 s9, v58, 16
	v_readlane_b32 s12, v58, 32
	v_readlane_b32 s13, v58, 48
	s_nop 0
	v_mov_b32_e32 v58, s9
	v_add_f32_e32 v58, s8, v58
	v_mov_b32_e32 v59, s13
	v_add_f32_e32 v59, s12, v59
	v_add_f32_e32 v58, v58, v59
	s_nop 0
	v_readlane_b32 s8, v70, 0
	v_readlane_b32 s9, v70, 16
	v_readlane_b32 s12, v70, 32
	v_readlane_b32 s13, v70, 48
	s_nop 0
	v_mov_b32_e32 v70, s9
	v_add_f32_e32 v70, s8, v70
	v_mov_b32_e32 v71, s13
	v_add_f32_e32 v71, s12, v71
	v_add_f32_e32 v70, v70, v71
	v_fmamk_f32 v22, v22, 0x3c000000, v186
	v_rsq_f32_e32 v22, v22
	s_nop 0
	v_fmamk_f32 v34, v34, 0x3c000000, v186
	v_rsq_f32_e32 v34, v34
	s_nop 0
	v_fmamk_f32 v46, v46, 0x3c000000, v186
	v_rsq_f32_e32 v46, v46
	s_nop 0
	v_fmamk_f32 v58, v58, 0x3c000000, v186
	v_rsq_f32_e32 v58, v58
	s_nop 0
	v_fmamk_f32 v70, v70, 0x3c000000, v186
	v_rsq_f32_e32 v70, v70
	s_nop 0
	v_pk_mul_f32 v[20:21], v[20:21], v[22:23] op_sel_hi:[1,0]
	v_pk_mul_f32 v[32:33], v[32:33], v[34:35] op_sel_hi:[1,0]
	v_pk_mul_f32 v[44:45], v[44:45], v[46:47] op_sel_hi:[1,0]
	v_pk_mul_f32 v[56:57], v[56:57], v[58:59] op_sel_hi:[1,0]
	v_pk_mul_f32 v[68:69], v[68:69], v[70:71] op_sel_hi:[1,0]
	s_mov_b32 s12, s22
	s_mul_hi_u32 s13, s12, 0x66666667
; __device__ __forceinline__ bf16_t f2bf(float x) { return (bf16_t)(cvt_pk_bf16(x, x) & 0xffffu); }
; __global__ void __launch_bounds__(512) mk_fwd(Params P) {
;     ...
;                 x0 = x0 * rinv * (slot < 8 ? gq0 : gk0); x1 = x1 * rinv * (slot < 8 ? gq1 : gk1);
;                 if (rr >= CTXL) { const int t = rr - CTXL, pr = t >> 6, pc = t & 63;
;                     const float c0 = tab[(pr * 32 + jj) * 2], s0 = tab[(pr * 32 + jj) * 2 + 1], c1 = tab[(pc * 32 + jj) * 2], s1 = tab[(pc * 32 + jj) * 2 + 1];
;                     const float y0 = __shfl_xor(x0, 32), y1 = __shfl_xor(x1, 32);
;                     x0 = lane < 32 ? x0 * c0 - y0 * s0 : x0 * c0 + y0 * s0;
;                     x1 = lane < 32 ? x1 * c1 - y1 * s1 : x1 * c1 + y1 * s1; }
;                 bf16_t* dst = slot < 8 ? Qb + (size_t)row * 2048 + slot * 128 : Kb + (size_t)row * 1024 + (slot - 8) * 128;
;                 dst[lane] = f2bf(x0); dst[lane + 64] = f2bf(x1); }
	s_lshr_b32 s13, s13, 2
	s_mul_i32 s9, s13, 10
	s_sub_u32 s9, s12, s9
	s_cmp_lt_u32 s9, 8
	s_cselect_b64 vcc, -1, 0
	v_cndmask_b32_e32 v22, v0, v2, vcc
	v_cndmask_b32_e32 v23, v1, v3, vcc
	v_pk_mul_f32 v[20:21], v[22:23], v[20:21]
	s_mul_i32 s12, s42, 1
	s_add_u32 s12, s22, s12
	s_mul_hi_u32 s13, s12, 0x66666667
	s_lshr_b32 s13, s13, 2
	s_mul_i32 s9, s13, 10
	s_sub_u32 s9, s12, s9
	s_cmp_lt_u32 s9, 8
	s_cselect_b64 vcc, -1, 0
	v_cndmask_b32_e32 v34, v0, v2, vcc
	v_cndmask_b32_e32 v35, v1, v3, vcc
	v_pk_mul_f32 v[32:33], v[34:35], v[32:33]
	s_mul_i32 s12, s42, 2
	s_add_u32 s12, s22, s12
	s_mul_hi_u32 s13, s12, 0x66666667
	s_lshr_b32 s13, s13, 2
	s_mul_i32 s9, s13, 10
	s_sub_u32 s9, s12, s9
	s_cmp_lt_u32 s9, 8
	s_cselect_b64 vcc, -1, 0
	v_cndmask_b32_e32 v46, v0, v2, vcc
	v_cndmask_b32_e32 v47, v1, v3, vcc
	v_pk_mul_f32 v[44:45], v[46:47], v[44:45]
	s_mul_i32 s12, s42, 3
	s_add_u32 s12, s22, s12
	s_mul_hi_u32 s13, s12, 0x66666667
	s_lshr_b32 s13, s13, 2
	s_mul_i32 s9, s13, 10
	s_sub_u32 s9, s12, s9
	s_cmp_lt_u32 s9, 8
	s_cselect_b64 vcc, -1, 0
	v_cndmask_b32_e32 v58, v0, v2, vcc
	v_cndmask_b32_e32 v59, v1, v3, vcc
	v_pk_mul_f32 v[56:57], v[58:59], v[56:57]
	s_mul_i32 s12, s42, 4
	s_add_u32 s12, s22, s12
	s_mul_hi_u32 s13, s12, 0x66666667
	s_lshr_b32 s13, s13, 2
	s_mul_i32 s9, s13, 10
	s_sub_u32 s9, s12, s9
	s_cmp_lt_u32 s9, 8
	s_cselect_b64 vcc, -1, 0
	v_cndmask_b32_e32 v70, v0, v2, vcc
	v_cndmask_b32_e32 v71, v1, v3, vcc
	v_pk_mul_f32 v[68:69], v[70:71], v[68:69]
	ds_bpermute_b32 v28, v12, v20
	ds_bpermute_b32 v29, v12, v21
	ds_bpermute_b32 v40, v12, v32
	ds_bpermute_b32 v41, v12, v33
	ds_bpermute_b32 v52, v12, v44
	ds_bpermute_b32 v53, v12, v45
	ds_bpermute_b32 v64, v12, v56
	ds_bpermute_b32 v65, v12, v57
	ds_bpermute_b32 v76, v12, v68
	ds_bpermute_b32 v77, v12, v69
	v_mov_b32_e32 v22, v24
	v_mov_b32_e32 v23, v26
	v_mov_b32_e32 v24, v25
	v_mov_b32_e32 v25, v27
	s_waitcnt lgkmcnt(0)
	v_pk_mul_f32 v[28:29], v[24:25], v[28:29]
	s_nop 0
	v_cndmask_b32_e64 v29, v29, -v29, s[6:7]
	v_cndmask_b32_e64 v28, v28, -v28, s[6:7]
	v_pk_fma_f32 v[30:31], v[20:21], v[22:23], v[28:29]
	v_mov_b32_e32 v34, v36
	v_mov_b32_e32 v35, v38
	v_mov_b32_e32 v36, v37
	v_mov_b32_e32 v37, v39
	s_waitcnt lgkmcnt(0)
	v_pk_mul_f32 v[40:41], v[36:37], v[40:41]
	s_nop 0
	v_cndmask_b32_e64 v41, v41, -v41, s[6:7]
	v_cndmask_b32_e64 v40, v40, -v40, s[6:7]
	v_pk_fma_f32 v[42:43], v[32:33], v[34:35], v[40:41]
	v_mov_b32_e32 v46, v48
	v_mov_b32_e32 v47, v50
	v_mov_b32_e32 v48, v49
	v_mov_b32_e32 v49, v51
	s_waitcnt lgkmcnt(0)
	v_pk_mul_f32 v[52:53], v[48:49], v[52:53]
	s_nop 0
	v_cndmask_b32_e64 v53, v53, -v53, s[6:7]
	v_cndmask_b32_e64 v52, v52, -v52, s[6:7]
	v_pk_fma_f32 v[54:55], v[44:45], v[46:47], v[52:53]
	v_mov_b32_e32 v58, v60
	v_mov_b32_e32 v59, v62
	v_mov_b32_e32 v60, v61
	v_mov_b32_e32 v61, v63
	s_waitcnt lgkmcnt(0)
	v_pk_mul_f32 v[64:65], v[60:61], v[64:65]
	s_nop 0
	v_cndmask_b32_e64 v65, v65, -v65, s[6:7]
	v_cndmask_b32_e64 v64, v64, -v64, s[6:7]
	v_pk_fma_f32 v[66:67], v[56:57], v[58:59], v[64:65]
	v_mov_b32_e32 v70, v72
	v_mov_b32_e32 v71, v74
	v_mov_b32_e32 v72, v73
	v_mov_b32_e32 v73, v75
	s_waitcnt lgkmcnt(0)
	v_pk_mul_f32 v[76:77], v[72:73], v[76:77]
	s_nop 0
	v_cndmask_b32_e64 v77, v77, -v77, s[6:7]
	v_cndmask_b32_e64 v76, v76, -v76, s[6:7]
	v_pk_fma_f32 v[78:79], v[68:69], v[70:71], v[76:77]
	s_mov_b32 s12, s22
	s_mul_hi_u32 s13, s12, 0x66666667
	s_lshr_b32 s13, s13, 2
	s_mul_i32 s9, s13, 10
	s_sub_u32 s9, s12, s9
	s_mul_hi_u32 s8, s12, 0x60606061
	s_lshr_b32 s8, s8, 14
	s_mul_i32 s8, s8, 0x1100
	s_sub_u32 s8, s13, s8
	s_sub_u32 s8, s8, 0x100
	s_cmp_ge_i32 s8, 0
	s_cselect_b64 s[12:13], -1, 0
	v_cndmask_b32_e64 v20, v20, v30, s[12:13]
	v_cndmask_b32_e64 v21, v21, v31, s[12:13]
	v_cvt_pk_bf16_f32 v30, v20, v20
	v_cvt_pk_bf16_f32 v31, v21, v21
	s_mul_i32 s12, s42, 1
	s_add_u32 s12, s22, s12
	s_mul_hi_u32 s13, s12, 0x66666667
	s_lshr_b32 s13, s13, 2
	s_mul_i32 s9, s13, 10
	s_sub_u32 s9, s12, s9
	s_mul_hi_u32 s8, s12, 0x60606061
	s_lshr_b32 s8, s8, 14
	s_mul_i32 s8, s8, 0x1100
	s_sub_u32 s8, s13, s8
	s_sub_u32 s8, s8, 0x100
	s_cmp_ge_i32 s8, 0
	s_cselect_b64 s[12:13], -1, 0
	v_cndmask_b32_e64 v32, v32, v42, s[12:13]
	v_cndmask_b32_e64 v33, v33, v43, s[12:13]
	v_cvt_pk_bf16_f32 v42, v32, v32
	v_cvt_pk_bf16_f32 v43, v33, v33
	s_mul_i32 s12, s42, 2
	s_add_u32 s12, s22, s12
	s_mul_hi_u32 s13, s12, 0x66666667
	s_lshr_b32 s13, s13, 2
	s_mul_i32 s9, s13, 10
	s_sub_u32 s9, s12, s9
	s_mul_hi_u32 s8, s12, 0x60606061
	s_lshr_b32 s8, s8, 14
	s_mul_i32 s8, s8, 0x1100
	s_sub_u32 s8, s13, s8
	s_sub_u32 s8, s8, 0x100
	s_cmp_ge_i32 s8, 0
	s_cselect_b64 s[12:13], -1, 0
	v_cndmask_b32_e64 v44, v44, v54, s[12:13]
	v_cndmask_b32_e64 v45, v45, v55, s[12:13]
	v_cvt_pk_bf16_f32 v54, v44, v44
	v_cvt_pk_bf16_f32 v55, v45, v45
	s_mul_i32 s12, s42, 3
	s_add_u32 s12, s22, s12
	s_mul_hi_u32 s13, s12, 0x66666667
	s_lshr_b32 s13, s13, 2
	s_mul_i32 s9, s13, 10
	s_sub_u32 s9, s12, s9
	s_mul_hi_u32 s8, s12, 0x60606061
	s_lshr_b32 s8, s8, 14
	s_mul_i32 s8, s8, 0x1100
	s_sub_u32 s8, s13, s8
	s_sub_u32 s8, s8, 0x100
	s_cmp_ge_i32 s8, 0
	s_cselect_b64 s[12:13], -1, 0
	v_cndmask_b32_e64 v56, v56, v66, s[12:13]
	v_cndmask_b32_e64 v57, v57, v67, s[12:13]
	v_cvt_pk_bf16_f32 v66, v56, v56
	v_cvt_pk_bf16_f32 v67, v57, v57
	s_mul_i32 s12, s42, 4
	s_add_u32 s12, s22, s12
	s_mul_hi_u32 s13, s12, 0x66666667
	s_lshr_b32 s13, s13, 2
	s_mul_i32 s9, s13, 10
	s_sub_u32 s9, s12, s9
	s_mul_hi_u32 s8, s12, 0x60606061
	s_lshr_b32 s8, s8, 14
	s_mul_i32 s8, s8, 0x1100
	s_sub_u32 s8, s13, s8
	s_sub_u32 s8, s8, 0x100
	s_cmp_ge_i32 s8, 0
	s_cselect_b64 s[12:13], -1, 0
	v_cndmask_b32_e64 v68, v68, v78, s[12:13]
	v_cndmask_b32_e64 v69, v69, v79, s[12:13]
	v_cvt_pk_bf16_f32 v78, v68, v68
	v_cvt_pk_bf16_f32 v79, v69, v69
	s_mov_b32 s12, s22
	s_mul_hi_u32 s13, s12, 0x66666667
	s_lshr_b32 s13, s13, 2
	s_mul_i32 s9, s13, 10
	s_sub_u32 s9, s12, s9
	s_lshl_b32 s8, s9, 8
	s_cmp_lt_u32 s9, 8
	s_cbranch_scc0 .Lgq_b_kdst0
	s_lshl_b32 s14, s13, 12
	s_add_u32 s14, s14, s8
	s_add_u32 s14, s3, s14
	s_addc_u32 s15, s20, 0
	s_branch .Lgq_b_st0
.Lgq_b_kdst0:
	s_lshl_b32 s14, s13, 11
	s_add_u32 s14, s14, s8
	s_add_u32 s14, s14, 0x14768800
	s_add_u32 s14, s0, s14
	s_addc_u32 s15, s1, 0
.Lgq_b_st0:
	global_store_short v6, v30, s[14:15]
	global_store_short v6, v31, s[14:15] offset:128
	s_mul_i32 s12, s42, 1
	s_add_u32 s12, s22, s12
	s_mul_hi_u32 s13, s12, 0x66666667
	s_lshr_b32 s13, s13, 2
	s_mul_i32 s9, s13, 10
	s_sub_u32 s9, s12, s9
	s_lshl_b32 s8, s9, 8
	s_cmp_lt_u32 s9, 8
	s_cbranch_scc0 .Lgq_b_kdst1
	s_lshl_b32 s14, s13, 12
	s_add_u32 s14, s14, s8
	s_add_u32 s14, s3, s14
	s_addc_u32 s15, s20, 0
	s_branch .Lgq_b_st1

; __device__ __forceinline__ bf16_t f2bf(float x) { return (bf16_t)(cvt_pk_bf16(x, x) & 0xffffu); }
; __global__ void __launch_bounds__(512) mk_fwd(Params P) {
;     ...
;                 bf16_t* dst = slot < 8 ? Qb + (size_t)row * 2048 + slot * 128 : Kb + (size_t)row * 1024 + (slot - 8) * 128;
;                 dst[lane] = f2bf(x0); dst[lane + 64] = f2bf(x1); }
.Lgq_b_st1:
	global_store_short v6, v42, s[14:15]
	global_store_short v6, v43, s[14:15] offset:128
	s_mul_i32 s12, s42, 2
	s_add_u32 s12, s22, s12
	s_mul_hi_u32 s13, s12, 0x66666667
	s_lshr_b32 s13, s13, 2
	s_mul_i32 s9, s13, 10
	s_sub_u32 s9, s12, s9
	s_lshl_b32 s8, s9, 8
	s_cmp_lt_u32 s9, 8
	s_cbranch_scc0 .Lgq_b_kdst2
	s_lshl_b32 s14, s13, 12
	s_add_u32 s14, s14, s8
	s_add_u32 s14, s3, s14
	s_addc_u32 s15, s20, 0
	s_branch .Lgq_b_st2

; __device__ __forceinline__ bf16_t f2bf(float x) { return (bf16_t)(cvt_pk_bf16(x, x) & 0xffffu); }
; __global__ void __launch_bounds__(512) mk_fwd(Params P) {
;     ...
;                 bf16_t* dst = slot < 8 ? Qb + (size_t)row * 2048 + slot * 128 : Kb + (size_t)row * 1024 + (slot - 8) * 128;
;                 dst[lane] = f2bf(x0); dst[lane + 64] = f2bf(x1); }
.Lgq_b_st2:
	global_store_short v6, v54, s[14:15]
	global_store_short v6, v55, s[14:15] offset:128
	s_mul_i32 s12, s42, 3
	s_add_u32 s12, s22, s12
	s_mul_hi_u32 s13, s12, 0x66666667
	s_lshr_b32 s13, s13, 2
	s_mul_i32 s9, s13, 10
	s_sub_u32 s9, s12, s9
	s_lshl_b32 s8, s9, 8
	s_cmp_lt_u32 s9, 8
	s_cbranch_scc0 .Lgq_b_kdst3
	s_lshl_b32 s14, s13, 12
	s_add_u32 s14, s14, s8
	s_add_u32 s14, s3, s14
	s_addc_u32 s15, s20, 0
	s_branch .Lgq_b_st3

; __device__ __forceinline__ bf16_t f2bf(float x) { return (bf16_t)(cvt_pk_bf16(x, x) & 0xffffu); }
; __global__ void __launch_bounds__(512) mk_fwd(Params P) {
;     ...
;                 bf16_t* dst = slot < 8 ? Qb + (size_t)row * 2048 + slot * 128 : Kb + (size_t)row * 1024 + (slot - 8) * 128;
;                 dst[lane] = f2bf(x0); dst[lane + 64] = f2bf(x1); }
.Lgq_b_st3:
	global_store_short v6, v66, s[14:15]
	global_store_short v6, v67, s[14:15] offset:128
	s_mul_i32 s12, s42, 4
	s_add_u32 s12, s22, s12
	s_mul_hi_u32 s13, s12, 0x66666667
	s_lshr_b32 s13, s13, 2
	s_mul_i32 s9, s13, 10
	s_sub_u32 s9, s12, s9
	s_lshl_b32 s8, s9, 8
	s_cmp_lt_u32 s9, 8
	s_cbranch_scc0 .Lgq_b_kdst4
	s_lshl_b32 s14, s13, 12
	s_add_u32 s14, s14, s8
	s_add_u32 s14, s3, s14
	s_addc_u32 s15, s20, 0
	s_branch .Lgq_b_st4

; __device__ __forceinline__ bf16_t f2bf(float x) { return (bf16_t)(cvt_pk_bf16(x, x) & 0xffffu); }
; __global__ void __launch_bounds__(512) mk_fwd(Params P) {
;     ...
;             for (int it = gw; it < M * 10; it += NGW) { const int row = it / 10, slot = it - row * 10; const int bi = row / TB, rr = row - bi * TB;
;                 const float* src = QKR + (size_t)row * 1280 + slot * 128;
;                 float x0 = __builtin_nontemporal_load(&src[lane]), x1 = __builtin_nontemporal_load(&src[lane + 64]);
;                 const float rinv = rsqrtf(wave_sum(x0 * x0 + x1 * x1) * (1.f / 128.f) + EPS);
;                 x0 = x0 * rinv * (slot < 8 ? gq0 : gk0); x1 = x1 * rinv * (slot < 8 ? gq1 : gk1);
;                 if (rr >= CTXL) { const int t = rr - CTXL, pr = t >> 6, pc = t & 63;
;                     const float c0 = tab[(pr * 32 + jj) * 2], s0 = tab[(pr * 32 + jj) * 2 + 1], c1 = tab[(pc * 32 + jj) * 2], s1 = tab[(pc * 32 + jj) * 2 + 1];
;                     const float y0 = __shfl_xor(x0, 32), y1 = __shfl_xor(x1, 32);
;                     x0 = lane < 32 ? x0 * c0 - y0 * s0 : x0 * c0 + y0 * s0;
;                     x1 = lane < 32 ? x1 * c1 - y1 * s1 : x1 * c1 + y1 * s1; }
;                 bf16_t* dst = slot < 8 ? Qb + (size_t)row * 2048 + slot * 128 : Kb + (size_t)row * 1024 + (slot - 8) * 128;
;                 dst[lane] = f2bf(x0); dst[lane + 64] = f2bf(x1); }
.Lgq_b_st4:
	global_store_short v6, v78, s[14:15]
	global_store_short v6, v79, s[14:15] offset:128
	s_mul_i32 s8, s42, 5
	s_add_u32 s22, s22, s8
	s_branch .Lgq_batch_test
.Lgq_tail:
	s_cmp_lt_u32 s22, 0x2a800
	s_cbranch_scc0 .LBB0_42
	s_mov_b32 s12, s22
	s_mul_hi_u32 s13, s12, 0x66666667
	s_lshr_b32 s13, s13, 2
	s_mul_i32 s9, s13, 10
	s_sub_u32 s9, s12, s9
	s_lshl_b32 s14, s12, 9
	s_add_u32 s14, s90, s14
	s_addc_u32 s15, s91, 0
	global_load_dword v20, v4, s[14:15] nt
	global_load_dword v21, v4, s[14:15] offset:256 nt
	s_mul_hi_u32 s8, s12, 0x60606061
	s_lshr_b32 s8, s8, 14
	s_mul_i32 s8, s8, 0x1100
	s_sub_u32 s8, s13, s8
	s_sub_u32 s8, s8, 0x100
	s_cmp_ge_i32 s8, 0
	s_cbranch_scc0 .Lgq_t_nolat0
	s_lshr_b32 s14, s8, 6
	s_lshl_b32 s14, s14, 8
	s_add_u32 s14, s10, s14
	s_addc_u32 s15, s11, 0
	global_load_dwordx2 v[24:25], v9, s[14:15]
	s_and_b32 s14, s8, 63
	s_lshl_b32 s14, s14, 8
	s_add_u32 s14, s10, s14
	s_addc_u32 s15, s11, 0
	global_load_dwordx2 v[26:27], v9, s[14:15]
.Lgq_t_nolat0:
	s_waitcnt vmcnt(0)
	v_pk_mul_f32 v[22:23], v[20:21], v[20:21]
	v_add_f32_e32 v22, v22, v23
	s_nop 1
	v_add_f32_dpp v22, v22, v22 quad_perm:[1,0,3,2] row_mask:0xf bank_mask:0xf
	s_nop 1
	v_add_f32_dpp v22, v22, v22 quad_perm:[2,3,0,1] row_mask:0xf bank_mask:0xf
	s_nop 1
	v_add_f32_dpp v22, v22, v22 row_half_mirror row_mask:0xf bank_mask:0xf
	s_nop 1
	v_add_f32_dpp v22, v22, v22 row_mirror row_mask:0xf bank_mask:0xf
	s_nop 0
	v_readlane_b32 s8, v22, 0
	v_readlane_b32 s9, v22, 16
	v_readlane_b32 s12, v22, 32
	v_readlane_b32 s13, v22, 48
	s_nop 0
	v_mov_b32_e32 v22, s9
	v_add_f32_e32 v22, s8, v22
	v_mov_b32_e32 v23, s13
	v_add_f32_e32 v23, s12, v23
	v_add_f32_e32 v22, v22, v23
	v_fmamk_f32 v22, v22, 0x3c000000, v186
	v_rsq_f32_e32 v22, v22
	s_nop 0
	v_pk_mul_f32 v[20:21], v[20:21], v[22:23] op_sel_hi:[1,0]
	s_mov_b32 s12, s22
	s_mul_hi_u32 s13, s12, 0x66666667
	s_lshr_b32 s13, s13, 2
	s_mul_i32 s9, s13, 10
	s_sub_u32 s9, s12, s9
	s_cmp_lt_u32 s9, 8
	s_cselect_b64 vcc, -1, 0
	v_cndmask_b32_e32 v22, v0, v2, vcc
	v_cndmask_b32_e32 v23, v1, v3, vcc
	v_pk_mul_f32 v[20:21], v[22:23], v[20:21]
	ds_bpermute_b32 v28, v12, v20
	ds_bpermute_b32 v29, v12, v21
	v_mov_b32_e32 v22, v24
	v_mov_b32_e32 v23, v26
	v_mov_b32_e32 v24, v25
	v_mov_b32_e32 v25, v27
	s_waitcnt lgkmcnt(0)
	v_pk_mul_f32 v[28:29], v[24:25], v[28:29]
	s_nop 0
	v_cndmask_b32_e64 v29, v29, -v29, s[6:7]
	v_cndmask_b32_e64 v28, v28, -v28, s[6:7]
	v_pk_fma_f32 v[30:31], v[20:21], v[22:23], v[28:29]
	s_mov_b32 s12, s22
	s_mul_hi_u32 s13, s12, 0x66666667
	s_lshr_b32 s13, s13, 2
	s_mul_i32 s9, s13, 10
	s_sub_u32 s9, s12, s9
	s_mul_hi_u32 s8, s12, 0x60606061
	s_lshr_b32 s8, s8, 14
	s_mul_i32 s8, s8, 0x1100
	s_sub_u32 s8, s13, s8
	s_sub_u32 s8, s8, 0x100
	s_cmp_ge_i32 s8, 0
	s_cselect_b64 s[12:13], -1, 0
	v_cndmask_b32_e64 v20, v20, v30, s[12:13]
	v_cndmask_b32_e64 v21, v21, v31, s[12:13]
	v_cvt_pk_bf16_f32 v30, v20, v20
	v_cvt_pk_bf16_f32 v31, v21, v21
	s_mov_b32 s12, s22
	s_mul_hi_u32 s13, s12, 0x66666667
	s_lshr_b32 s13, s13, 2
	s_mul_i32 s9, s13, 10
	s_sub_u32 s9, s12, s9
	s_lshl_b32 s8, s9, 8
	s_cmp_lt_u32 s9, 8
	s_cbranch_scc0 .Lgq_t_kdst0
	s_lshl_b32 s14, s13, 12
	s_add_u32 s14, s14, s8
	s_add_u32 s14, s3, s14
	s_addc_u32 s15, s20, 0
	s_branch .Lgq_t_st0

; __device__ __forceinline__ bf16_t f2bf(float x) { return (bf16_t)(cvt_pk_bf16(x, x) & 0xffffu); }
; __global__ void __launch_bounds__(512) mk_fwd(Params P) {
;     ...
;                 bf16_t* dst = slot < 8 ? Qb + (size_t)row * 2048 + slot * 128 : Kb + (size_t)row * 1024 + (slot - 8) * 128;
;                 dst[lane] = f2bf(x0); dst[lane + 64] = f2bf(x1); }
.Lgq_t_st0:
	global_store_short v6, v30, s[14:15]
	global_store_short v6, v31, s[14:15] offset:128
	s_add_u32 s22, s22, s42
	s_branch .Lgq_tail
